# pool mixer rewritten: window sums from 31 register-held rows, 64x64x64 mixer on f32 MFMA 16x16x4 with W^T and pool_scale register-resident; layer-loop back-edges via trampolines
# speedup vs baseline: 1.1848x; 1.0267x over previous
; DI unsigned pk2(float lo, float hi) { f32x2 v = {lo, hi}; bf16x2_t r = __builtin_convertvector(v, bf16x2_t); return __builtin_bit_cast(unsigned, r); }
; DI void phase_pool(const Params& p, int l, char* smem) {
;     ...
;         {
;             const int t = tid >> 2, dq = (tid & 3) * 16;
;             float acc[16];
; #pragma unroll
;             for (int j = 0; j < 16; ++j) acc[j] = 0.f;
;             for (int c = 0; c < 64; ++c) {
;                 const float dv = sd[t * 65 + c];
; #pragma unroll
;                 for (int j4 = 0; j4 < 4; ++j4) {
;                     const f32x4 w4 = *(const f32x4*)(sw + c * 64 + dq + j4 * 4);
;                     acc[j4 * 4 + 0] += dv * w4[0]; acc[j4 * 4 + 1] += dv * w4[1]; acc[j4 * 4 + 2] += dv * w4[2]; acc[j4 * 4 + 3] += dv * w4[3];
;                 }
;             }
;             const float* sc = p.pool_scale + l * 256 + gi * 64 + dq;
;             u32x4 o0, o1;
; #pragma unroll
;             for (int j = 0; j < 4; ++j) { o0[j] = pk2(acc[2 * j] * sc[2 * j], acc[2 * j + 1] * sc[2 * j + 1]); o1[j] = pk2(acc[8 + 2 * j] * sc[8 + 2 * j], acc[9 + 2 * j] * sc[9 + 2 * j]); }
;             bf16_t* dst = p.hy + (n0 + t) * DM + 768 + gi * 64 + dq;
.LBB0_374:
	s_or_b64 exec, exec, s[10:11]
	v_readlane_b32 s52, v251, 51
	v_readlane_b32 s53, v251, 52
	v_readlane_b32 s54, v251, 53
	v_readlane_b32 s55, v251, 54
	v_readlane_b32 s60, v251, 59
	v_readlane_b32 s61, v251, 60
	v_lshlrev_b32_e32 v20, 2, v31
	s_lshl_b32 s30, s42, 8
	v_readlane_b32 s62, v251, 61
	v_readlane_b32 s63, v251, 62
	s_mov_b64 s[52:53], s[60:61]
	s_lshl_b32 s13, s42, 14
	v_lshrrev_b32_e32 v22, 6, v31
	v_and_b32_e32 v23, 15, v31
	v_lshl_or_b32 v22, v22, 4, v23
	v_and_b32_e32 v39, 0xfc, v20
	s_lshl_b64 s[14:15], s[30:31], 2
	s_mov_b64 s[54:55], s[62:63]
	v_readlane_b32 s12, v249, 26
	v_and_b32_e32 v34, 48, v31
	v_mul_u32_u24_e32 v35, 0x110, v22
	s_add_u32 s14, s54, s14
	v_readlane_b32 s12, v249, 27
	v_lshlrev_b32_e32 v36, 5, v31
	v_lshlrev_b32_e32 v37, 5, v21
	v_lshlrev_b32_e32 v38, 5, v25
	v_add_u32_e32 v50, 0, v24
	v_add_u32_e32 v24, 0x400, v20
	v_add_u32_e32 v26, 0x800, v20
	v_add_u32_e32 v28, 0xc00, v20
	s_addc_u32 s15, s55, s15
	v_lshlrev_b32_e32 v188, 2, v34
	v_add_u32_e32 v52, s12, v35
	v_add_u32_e32 v52, v52, v34
	v_lshrrev_b32_e32 v51, 6, v31
	v_mul_u32_u24_e32 v51, 0x1100, v51
	v_add3_u32 v51, v51, s12, v39
	v_and_b32_e32 v35, 3, v31
	v_readlane_b32 s12, v249, 28
	v_cmp_gt_i32_e64 s[10:11], s35, v31
	v_ashrrev_i32_e32 v23, 31, v22
	v_ashrrev_i32_e32 v21, 31, v20
	v_ashrrev_i32_e32 v25, 31, v24
	v_ashrrev_i32_e32 v27, 31, v26
	v_ashrrev_i32_e32 v29, 31, v28
	v_add_u32_e32 v30, 0, v39
	v_lshl_add_u64 v[32:33], s[14:15], 0, v[188:189]
	v_lshrrev_b32_e32 v53, 6, v31
	v_lshl_add_u32 v53, v53, 12, v39
	s_mov_b32 s22, -1
	v_add_u32_e32 v54, 0, v36
	v_add_u32_e32 v55, 0, v37
	v_add_u32_e32 v56, 0, v38
	v_lshlrev_b32_e32 v188, 1, v34
	s_mov_b32 s20, s2
	v_readlane_b32 s56, v251, 55
	v_readlane_b32 s57, v251, 56
	v_readlane_b32 s58, v251, 57
	v_readlane_b32 s59, v251, 58
	v_readlane_b32 s64, v251, 63
	v_readlane_b32 s65, v252, 0
	v_readlane_b32 s66, v252, 1
	v_readlane_b32 s67, v252, 2

; DI void phase_pool(const Params& p, int l, char* smem) {
;     ...
;         if (gi != gi_loaded) {
; #pragma unroll
;             for (int k = 0; k < 4; ++k) *(f32x4*)(sw + (tid + 256 * k) * 4) = *(const f32x4*)(p.pool_w + ((size_t)(l * 4 + gi) * 64) * 64 + (tid + 256 * k) * 4);
;             gi_loaded = gi;
;         }
;     ...
;             const float* sc = p.pool_scale + l * 256 + gi * 64 + dq;
.LBB0_379:
	s_lshl_b32 s14, s23, 12
	v_readlane_b32 s52, v251, 51
	s_or_b32 s30, s14, s13
	v_readlane_b32 s53, v251, 52
	v_readlane_b32 s54, v251, 53
	v_readlane_b32 s55, v251, 54
	v_readlane_b32 s60, v251, 59
	v_readlane_b32 s61, v251, 60
	s_lshl_b64 s[14:15], s[30:31], 2
	v_readlane_b32 s62, v251, 61
	v_readlane_b32 s63, v251, 62
	s_mov_b64 s[52:53], s[60:61]
	s_add_u32 s14, s52, s14
	s_addc_u32 s15, s53, s15
	s_waitcnt vmcnt(0)
	v_and_b32_e32 v57, 15, v31
	v_lshrrev_b32_e32 v74, 2, v57
	v_and_b32_e32 v75, 3, v57
	v_lshl_add_u32 v75, v74, 4, v75
	v_bfe_u32 v74, v31, 4, 2
	v_lshlrev_b32_e32 v75, 2, v75
	v_lshl_add_u32 v57, v74, 10, v75
	global_load_dword v77, v57, s[14:15] offset:0
	global_load_dword v78, v57, s[14:15] offset:16
	global_load_dword v79, v57, s[14:15] offset:32
	global_load_dword v80, v57, s[14:15] offset:48
	global_load_dword v81, v57, s[14:15] offset:256
	global_load_dword v82, v57, s[14:15] offset:272
	global_load_dword v83, v57, s[14:15] offset:288
	global_load_dword v84, v57, s[14:15] offset:304
	global_load_dword v85, v57, s[14:15] offset:512
	global_load_dword v86, v57, s[14:15] offset:528
	global_load_dword v87, v57, s[14:15] offset:544
	global_load_dword v88, v57, s[14:15] offset:560
	global_load_dword v89, v57, s[14:15] offset:768
	global_load_dword v90, v57, s[14:15] offset:784
	global_load_dword v91, v57, s[14:15] offset:800
	global_load_dword v92, v57, s[14:15] offset:816
	v_add_u32_e32 v57, 0x1000, v57
	global_load_dword v93, v57, s[14:15] offset:0
	global_load_dword v94, v57, s[14:15] offset:16
	global_load_dword v95, v57, s[14:15] offset:32
	global_load_dword v96, v57, s[14:15] offset:48
	global_load_dword v97, v57, s[14:15] offset:256
	global_load_dword v98, v57, s[14:15] offset:272
	global_load_dword v99, v57, s[14:15] offset:288
	global_load_dword v100, v57, s[14:15] offset:304
	global_load_dword v101, v57, s[14:15] offset:512
	global_load_dword v102, v57, s[14:15] offset:528
	global_load_dword v103, v57, s[14:15] offset:544
	global_load_dword v104, v57, s[14:15] offset:560
	global_load_dword v105, v57, s[14:15] offset:768
	global_load_dword v106, v57, s[14:15] offset:784
	global_load_dword v107, v57, s[14:15] offset:800
	global_load_dword v108, v57, s[14:15] offset:816
	v_add_u32_e32 v57, 0x1000, v57
	global_load_dword v109, v57, s[14:15] offset:0
	global_load_dword v110, v57, s[14:15] offset:16
	global_load_dword v111, v57, s[14:15] offset:32
	global_load_dword v112, v57, s[14:15] offset:48
	global_load_dword v113, v57, s[14:15] offset:256
	global_load_dword v114, v57, s[14:15] offset:272
	global_load_dword v115, v57, s[14:15] offset:288
	global_load_dword v116, v57, s[14:15] offset:304
	global_load_dword v117, v57, s[14:15] offset:512
	global_load_dword v118, v57, s[14:15] offset:528
	global_load_dword v119, v57, s[14:15] offset:544
	global_load_dword v120, v57, s[14:15] offset:560
	global_load_dword v121, v57, s[14:15] offset:768
	global_load_dword v122, v57, s[14:15] offset:784
	global_load_dword v123, v57, s[14:15] offset:800
	global_load_dword v124, v57, s[14:15] offset:816
	v_add_u32_e32 v57, 0x1000, v57
	global_load_dword v125, v57, s[14:15] offset:0
	global_load_dword v126, v57, s[14:15] offset:16
	global_load_dword v127, v57, s[14:15] offset:32
	global_load_dword v128, v57, s[14:15] offset:48
	global_load_dword v129, v57, s[14:15] offset:256
	global_load_dword v130, v57, s[14:15] offset:272
	global_load_dword v131, v57, s[14:15] offset:288
	global_load_dword v132, v57, s[14:15] offset:304
	global_load_dword v133, v57, s[14:15] offset:512
	global_load_dword v134, v57, s[14:15] offset:528
	global_load_dword v135, v57, s[14:15] offset:544
	global_load_dword v136, v57, s[14:15] offset:560
	global_load_dword v137, v57, s[14:15] offset:768
	global_load_dword v138, v57, s[14:15] offset:784
	global_load_dword v139, v57, s[14:15] offset:800
	global_load_dword v140, v57, s[14:15] offset:816
	v_readlane_b32 s56, v251, 55
	v_readlane_b32 s57, v251, 56
	v_readlane_b32 s58, v251, 57
	v_readlane_b32 s59, v251, 58
	v_readlane_b32 s64, v251, 63
	v_readlane_b32 s65, v252, 0
	v_readlane_b32 s66, v252, 1
	v_readlane_b32 s67, v252, 2
	s_mov_b64 s[54:55], s[62:63]
	s_mov_b32 s22, s23
	s_lshl_b32 s30, s23, 8
	v_lshl_add_u64 v[74:75], v[32:33], 0, s[30:31]
	global_load_dwordx4 v[142:145], v[74:75], off offset:0
	global_load_dwordx4 v[146:149], v[74:75], off offset:16
	global_load_dwordx4 v[150:153], v[74:75], off offset:32
	global_load_dwordx4 v[154:157], v[74:75], off offset:48

; DI void phase_pool(const Params& p, int l, char* smem) {
;     ...
;         __syncthreads();
;         for (int i = tid; i < 4096; i += 256) {
;             const int t = i >> 6, c = i & 63; const int tb = tb0 + t;
;             float s_ = 0.f;
;             for (int k = 0; k < w; ++k) s_ += su[(15 + t - k) * 64 + c];
;             const float cnt = (float)(tb + 1 < w ? tb + 1 : w);
;             sd[t * 65 + c] = s_ / cnt - su[(15 + t) * 64 + c];
.LBB0_386:
	s_or_b64 exec, exec, s[18:19]
	s_ashr_i32 s16, s20, 2
	s_ashr_i32 s17, s16, 31
	s_lshl_b64 s[16:17], s[16:17], 6
	s_waitcnt lgkmcnt(0)
	s_barrier
	ds_read_b32 v174, v53 offset:0
	ds_read_b32 v175, v53 offset:256
	ds_read_b32 v176, v53 offset:512
	ds_read_b32 v177, v53 offset:768
	ds_read_b32 v178, v53 offset:1024
	ds_read_b32 v179, v53 offset:1280
	ds_read_b32 v180, v53 offset:1536
	ds_read_b32 v181, v53 offset:1792
	ds_read_b32 v182, v53 offset:2048
	ds_read_b32 v183, v53 offset:2304
	ds_read_b32 v184, v53 offset:2560
	ds_read_b32 v185, v53 offset:2816
	ds_read_b32 v186, v53 offset:3072
	ds_read_b32 v187, v53 offset:3328
	ds_read_b32 v191, v53 offset:3584
	ds_read_b32 v192, v53 offset:3840
	ds_read_b32 v193, v53 offset:4096
	ds_read_b32 v194, v53 offset:4352
	ds_read_b32 v195, v53 offset:4608
	ds_read_b32 v196, v53 offset:4864
	ds_read_b32 v197, v53 offset:5120
	ds_read_b32 v198, v53 offset:5376
	ds_read_b32 v199, v53 offset:5632
	ds_read_b32 v200, v53 offset:5888
	ds_read_b32 v201, v53 offset:6144
	ds_read_b32 v202, v53 offset:6400
	ds_read_b32 v203, v53 offset:6656
	ds_read_b32 v204, v53 offset:6912
	ds_read_b32 v205, v53 offset:7168
	ds_read_b32 v206, v53 offset:7424
	ds_read_b32 v207, v53 offset:7680
	s_and_b32 s20, s16, 0x3fc0
	s_lshl_b32 s25, 2, s23
	s_or_b32 s26, s20, 1
	v_lshrrev_b32_e32 v57, 6, v31
	v_lshl_add_u32 v57, v57, 4, s26
	s_waitcnt lgkmcnt(0)
	v_add_f32_e32 v34, 0, v192
	v_add_f32_e32 v35, 0, v193
	v_add_f32_e32 v36, 0, v194
	v_add_f32_e32 v37, 0, v195
	v_add_f32_e32 v38, 0, v196
	v_add_f32_e32 v39, 0, v197
	v_add_f32_e32 v40, 0, v198
	v_add_f32_e32 v41, 0, v199
	v_add_f32_e32 v42, 0, v200
	v_add_f32_e32 v43, 0, v201
	v_add_f32_e32 v44, 0, v202
	v_add_f32_e32 v45, 0, v203
	v_add_f32_e32 v46, 0, v204
	v_add_f32_e32 v47, 0, v205
	v_add_f32_e32 v48, 0, v206
	v_add_f32_e32 v49, 0, v207
	v_add_f32_e32 v34, v34, v191
	v_add_f32_e32 v35, v35, v192
	v_add_f32_e32 v36, v36, v193
	v_add_f32_e32 v37, v37, v194
	v_add_f32_e32 v38, v38, v195
	v_add_f32_e32 v39, v39, v196
	v_add_f32_e32 v40, v40, v197
	v_add_f32_e32 v41, v41, v198
	v_add_f32_e32 v42, v42, v199
	v_add_f32_e32 v43, v43, v200
	v_add_f32_e32 v44, v44, v201
	v_add_f32_e32 v45, v45, v202
	v_add_f32_e32 v46, v46, v203
	v_add_f32_e32 v47, v47, v204
	v_add_f32_e32 v48, v48, v205
	v_add_f32_e32 v49, v49, v206
	s_cmp_eq_u32 s23, 0
	s_cbranch_scc1 .Lpool_div
	v_add_f32_e32 v34, v34, v187
	v_add_f32_e32 v35, v35, v191
	v_add_f32_e32 v36, v36, v192
	v_add_f32_e32 v37, v37, v193
	v_add_f32_e32 v38, v38, v194
	v_add_f32_e32 v39, v39, v195
	v_add_f32_e32 v40, v40, v196
	v_add_f32_e32 v41, v41, v197
	v_add_f32_e32 v42, v42, v198
	v_add_f32_e32 v43, v43, v199
	v_add_f32_e32 v44, v44, v200
	v_add_f32_e32 v45, v45, v201
	v_add_f32_e32 v46, v46, v202
	v_add_f32_e32 v47, v47, v203
	v_add_f32_e32 v48, v48, v204
	v_add_f32_e32 v49, v49, v205
	v_add_f32_e32 v34, v34, v186
	v_add_f32_e32 v35, v35, v187
	v_add_f32_e32 v36, v36, v191
	v_add_f32_e32 v37, v37, v192
	v_add_f32_e32 v38, v38, v193
	v_add_f32_e32 v39, v39, v194
	v_add_f32_e32 v40, v40, v195
	v_add_f32_e32 v41, v41, v196
	v_add_f32_e32 v42, v42, v197
	v_add_f32_e32 v43, v43, v198
	v_add_f32_e32 v44, v44, v199
	v_add_f32_e32 v45, v45, v200
	v_add_f32_e32 v46, v46, v201
	v_add_f32_e32 v47, v47, v202
	v_add_f32_e32 v48, v48, v203
	v_add_f32_e32 v49, v49, v204
	s_cmp_eq_u32 s23, 1
	s_cbranch_scc1 .Lpool_div
	v_add_f32_e32 v34, v34, v185
	v_add_f32_e32 v35, v35, v186
	v_add_f32_e32 v36, v36, v187
	v_add_f32_e32 v37, v37, v191
	v_add_f32_e32 v38, v38, v192
	v_add_f32_e32 v39, v39, v193
	v_add_f32_e32 v40, v40, v194
	v_add_f32_e32 v41, v41, v195
	v_add_f32_e32 v42, v42, v196
	v_add_f32_e32 v43, v43, v197
	v_add_f32_e32 v44, v44, v198
	v_add_f32_e32 v45, v45, v199
	v_add_f32_e32 v46, v46, v200
	v_add_f32_e32 v47, v47, v201
	v_add_f32_e32 v48, v48, v202
	v_add_f32_e32 v49, v49, v203
	v_add_f32_e32 v34, v34, v184
	v_add_f32_e32 v35, v35, v185
	v_add_f32_e32 v36, v36, v186
	v_add_f32_e32 v37, v37, v187
	v_add_f32_e32 v38, v38, v191
	v_add_f32_e32 v39, v39, v192
	v_add_f32_e32 v40, v40, v193
	v_add_f32_e32 v41, v41, v194
	v_add_f32_e32 v42, v42, v195
	v_add_f32_e32 v43, v43, v196
	v_add_f32_e32 v44, v44, v197
	v_add_f32_e32 v45, v45, v198
	v_add_f32_e32 v46, v46, v199
	v_add_f32_e32 v47, v47, v200
	v_add_f32_e32 v48, v48, v201
	v_add_f32_e32 v49, v49, v202
	v_add_f32_e32 v34, v34, v183
	v_add_f32_e32 v35, v35, v184
	v_add_f32_e32 v36, v36, v185
	v_add_f32_e32 v37, v37, v186
	v_add_f32_e32 v38, v38, v187
	v_add_f32_e32 v39, v39, v191
	v_add_f32_e32 v40, v40, v192
	v_add_f32_e32 v41, v41, v193
	v_add_f32_e32 v42, v42, v194
	v_add_f32_e32 v43, v43, v195
	v_add_f32_e32 v44, v44, v196
	v_add_f32_e32 v45, v45, v197
	v_add_f32_e32 v46, v46, v198
	v_add_f32_e32 v47, v47, v199
	v_add_f32_e32 v48, v48, v200
	v_add_f32_e32 v49, v49, v201
	v_add_f32_e32 v34, v34, v182
	v_add_f32_e32 v35, v35, v183
	v_add_f32_e32 v36, v36, v184
	v_add_f32_e32 v37, v37, v185
	v_add_f32_e32 v38, v38, v186
	v_add_f32_e32 v39, v39, v187
	v_add_f32_e32 v40, v40, v191
	v_add_f32_e32 v41, v41, v192
	v_add_f32_e32 v42, v42, v193
	v_add_f32_e32 v43, v43, v194
	v_add_f32_e32 v44, v44, v195
	v_add_f32_e32 v45, v45, v196
	v_add_f32_e32 v46, v46, v197
	v_add_f32_e32 v47, v47, v198
	v_add_f32_e32 v48, v48, v199
	v_add_f32_e32 v49, v49, v200
	s_cmp_eq_u32 s23, 2
	s_cbranch_scc1 .Lpool_div
; DI void phase_pool(const Params& p, int l, char* smem) {
;     ...
;         for (int i = tid; i < 4096; i += 256) {
;             const int t = i >> 6, c = i & 63; const int tb = tb0 + t;
;             float s_ = 0.f;
;             for (int k = 0; k < w; ++k) s_ += su[(15 + t - k) * 64 + c];
;             const float cnt = (float)(tb + 1 < w ? tb + 1 : w);
;             sd[t * 65 + c] = s_ / cnt - su[(15 + t) * 64 + c];
;         }
	v_add_f32_e32 v34, v34, v181
	v_add_f32_e32 v35, v35, v182
	v_add_f32_e32 v36, v36, v183
	v_add_f32_e32 v37, v37, v184
	v_add_f32_e32 v38, v38, v185
	v_add_f32_e32 v39, v39, v186
	v_add_f32_e32 v40, v40, v187
	v_add_f32_e32 v41, v41, v191
	v_add_f32_e32 v42, v42, v192
	v_add_f32_e32 v43, v43, v193
	v_add_f32_e32 v44, v44, v194
	v_add_f32_e32 v45, v45, v195
	v_add_f32_e32 v46, v46, v196
	v_add_f32_e32 v47, v47, v197
	v_add_f32_e32 v48, v48, v198
	v_add_f32_e32 v49, v49, v199
	v_add_f32_e32 v34, v34, v180
	v_add_f32_e32 v35, v35, v181
	v_add_f32_e32 v36, v36, v182
	v_add_f32_e32 v37, v37, v183
	v_add_f32_e32 v38, v38, v184
	v_add_f32_e32 v39, v39, v185
	v_add_f32_e32 v40, v40, v186
	v_add_f32_e32 v41, v41, v187
	v_add_f32_e32 v42, v42, v191
	v_add_f32_e32 v43, v43, v192
	v_add_f32_e32 v44, v44, v193
	v_add_f32_e32 v45, v45, v194
	v_add_f32_e32 v46, v46, v195
	v_add_f32_e32 v47, v47, v196
	v_add_f32_e32 v48, v48, v197
	v_add_f32_e32 v49, v49, v198
	v_add_f32_e32 v34, v34, v179
	v_add_f32_e32 v35, v35, v180
	v_add_f32_e32 v36, v36, v181
	v_add_f32_e32 v37, v37, v182
	v_add_f32_e32 v38, v38, v183
	v_add_f32_e32 v39, v39, v184
	v_add_f32_e32 v40, v40, v185
	v_add_f32_e32 v41, v41, v186
	v_add_f32_e32 v42, v42, v187
	v_add_f32_e32 v43, v43, v191
	v_add_f32_e32 v44, v44, v192
	v_add_f32_e32 v45, v45, v193
	v_add_f32_e32 v46, v46, v194
	v_add_f32_e32 v47, v47, v195
	v_add_f32_e32 v48, v48, v196
	v_add_f32_e32 v49, v49, v197
	v_add_f32_e32 v34, v34, v178
	v_add_f32_e32 v35, v35, v179
	v_add_f32_e32 v36, v36, v180
	v_add_f32_e32 v37, v37, v181
	v_add_f32_e32 v38, v38, v182
	v_add_f32_e32 v39, v39, v183
	v_add_f32_e32 v40, v40, v184
	v_add_f32_e32 v41, v41, v185
	v_add_f32_e32 v42, v42, v186
	v_add_f32_e32 v43, v43, v187
	v_add_f32_e32 v44, v44, v191
	v_add_f32_e32 v45, v45, v192
	v_add_f32_e32 v46, v46, v193
	v_add_f32_e32 v47, v47, v194
	v_add_f32_e32 v48, v48, v195
	v_add_f32_e32 v49, v49, v196
	v_add_f32_e32 v34, v34, v177
	v_add_f32_e32 v35, v35, v178
	v_add_f32_e32 v36, v36, v179
	v_add_f32_e32 v37, v37, v180
	v_add_f32_e32 v38, v38, v181
	v_add_f32_e32 v39, v39, v182
	v_add_f32_e32 v40, v40, v183
	v_add_f32_e32 v41, v41, v184
	v_add_f32_e32 v42, v42, v185
	v_add_f32_e32 v43, v43, v186
	v_add_f32_e32 v44, v44, v187
	v_add_f32_e32 v45, v45, v191
	v_add_f32_e32 v46, v46, v192
	v_add_f32_e32 v47, v47, v193
	v_add_f32_e32 v48, v48, v194
	v_add_f32_e32 v49, v49, v195
	v_add_f32_e32 v34, v34, v176
	v_add_f32_e32 v35, v35, v177
	v_add_f32_e32 v36, v36, v178
	v_add_f32_e32 v37, v37, v179
	v_add_f32_e32 v38, v38, v180
	v_add_f32_e32 v39, v39, v181
	v_add_f32_e32 v40, v40, v182
	v_add_f32_e32 v41, v41, v183
	v_add_f32_e32 v42, v42, v184
	v_add_f32_e32 v43, v43, v185
	v_add_f32_e32 v44, v44, v186
	v_add_f32_e32 v45, v45, v187
	v_add_f32_e32 v46, v46, v191
	v_add_f32_e32 v47, v47, v192
	v_add_f32_e32 v48, v48, v193
	v_add_f32_e32 v49, v49, v194
	v_add_f32_e32 v34, v34, v175
	v_add_f32_e32 v35, v35, v176
	v_add_f32_e32 v36, v36, v177
	v_add_f32_e32 v37, v37, v178
	v_add_f32_e32 v38, v38, v179
	v_add_f32_e32 v39, v39, v180
	v_add_f32_e32 v40, v40, v181
	v_add_f32_e32 v41, v41, v182
	v_add_f32_e32 v42, v42, v183
	v_add_f32_e32 v43, v43, v184
	v_add_f32_e32 v44, v44, v185
	v_add_f32_e32 v45, v45, v186
	v_add_f32_e32 v46, v46, v187
	v_add_f32_e32 v47, v47, v191
	v_add_f32_e32 v48, v48, v192
	v_add_f32_e32 v49, v49, v193
	v_add_f32_e32 v34, v34, v174
	v_add_f32_e32 v35, v35, v175
	v_add_f32_e32 v36, v36, v176
	v_add_f32_e32 v37, v37, v177
	v_add_f32_e32 v38, v38, v178
	v_add_f32_e32 v39, v39, v179
	v_add_f32_e32 v40, v40, v180
	v_add_f32_e32 v41, v41, v181
	v_add_f32_e32 v42, v42, v182
	v_add_f32_e32 v43, v43, v183
	v_add_f32_e32 v44, v44, v184
	v_add_f32_e32 v45, v45, v185
	v_add_f32_e32 v46, v46, v186
	v_add_f32_e32 v47, v47, v187
	v_add_f32_e32 v48, v48, v191
	v_add_f32_e32 v49, v49, v192
.Lpool_div:
	v_add_u32_e32 v60, 0, v57
	v_min_i32_e32 v60, s25, v60
	v_cvt_f32_i32_e32 v60, v60
	v_div_scale_f32 v61, s[28:29], v60, v60, v34
	v_rcp_f32_e32 v62, v61
	s_nop 0
	v_fma_f32 v63, -v61, v62, 1.0
	v_fmac_f32_e32 v62, v63, v62
	v_div_scale_f32 v63, vcc, v34, v60, v34
	v_mul_f32_e32 v64, v63, v62
	v_fma_f32 v65, -v61, v64, v63
	v_fmac_f32_e32 v64, v65, v62
	v_fma_f32 v61, -v61, v64, v63
	v_div_fmas_f32 v61, v61, v62, v64
	v_div_fixup_f32 v61, v61, v60, v34
	v_sub_f32_e32 v61, v61, v192
	ds_write_b32 v51, v61 offset:0
	v_add_u32_e32 v60, 1, v57
	v_min_i32_e32 v60, s25, v60
	v_cvt_f32_i32_e32 v60, v60
	v_div_scale_f32 v61, s[28:29], v60, v60, v35
	v_rcp_f32_e32 v62, v61
	s_nop 0
	v_fma_f32 v63, -v61, v62, 1.0
	v_fmac_f32_e32 v62, v63, v62
	v_div_scale_f32 v63, vcc, v35, v60, v35
	v_mul_f32_e32 v64, v63, v62
	v_fma_f32 v65, -v61, v64, v63
	v_fmac_f32_e32 v64, v65, v62
	v_fma_f32 v61, -v61, v64, v63
	v_div_fmas_f32 v61, v61, v62, v64
	v_div_fixup_f32 v61, v61, v60, v35
	v_sub_f32_e32 v61, v61, v193
	ds_write_b32 v51, v61 offset:272
	v_add_u32_e32 v60, 2, v57
	v_min_i32_e32 v60, s25, v60
	v_cvt_f32_i32_e32 v60, v60
	v_div_scale_f32 v61, s[28:29], v60, v60, v36
	v_rcp_f32_e32 v62, v61
	s_nop 0
	v_fma_f32 v63, -v61, v62, 1.0
	v_fmac_f32_e32 v62, v63, v62
	v_div_scale_f32 v63, vcc, v36, v60, v36
	v_mul_f32_e32 v64, v63, v62
	v_fma_f32 v65, -v61, v64, v63
	v_fmac_f32_e32 v64, v65, v62
	v_fma_f32 v61, -v61, v64, v63
	v_div_fmas_f32 v61, v61, v62, v64
	v_div_fixup_f32 v61, v61, v60, v36
	v_sub_f32_e32 v61, v61, v194
	ds_write_b32 v51, v61 offset:544
	v_add_u32_e32 v60, 3, v57
	v_min_i32_e32 v60, s25, v60
	v_cvt_f32_i32_e32 v60, v60
	v_div_scale_f32 v61, s[28:29], v60, v60, v37
	v_rcp_f32_e32 v62, v61
	s_nop 0
	v_fma_f32 v63, -v61, v62, 1.0
	v_fmac_f32_e32 v62, v63, v62
; DI void phase_pool(const Params& p, int l, char* smem) {
;     ...
;         for (int i = tid; i < 4096; i += 256) {
;             const int t = i >> 6, c = i & 63; const int tb = tb0 + t;
;             float s_ = 0.f;
;             for (int k = 0; k < w; ++k) s_ += su[(15 + t - k) * 64 + c];
;             const float cnt = (float)(tb + 1 < w ? tb + 1 : w);
;             sd[t * 65 + c] = s_ / cnt - su[(15 + t) * 64 + c];
;         }
;         __syncthreads();
	v_div_scale_f32 v63, vcc, v37, v60, v37
	v_mul_f32_e32 v64, v63, v62
	v_fma_f32 v65, -v61, v64, v63
	v_fmac_f32_e32 v64, v65, v62
	v_fma_f32 v61, -v61, v64, v63
	v_div_fmas_f32 v61, v61, v62, v64
	v_div_fixup_f32 v61, v61, v60, v37
	v_sub_f32_e32 v61, v61, v195
	ds_write_b32 v51, v61 offset:816
	v_add_u32_e32 v60, 4, v57
	v_min_i32_e32 v60, s25, v60
	v_cvt_f32_i32_e32 v60, v60
	v_div_scale_f32 v61, s[28:29], v60, v60, v38
	v_rcp_f32_e32 v62, v61
	s_nop 0
	v_fma_f32 v63, -v61, v62, 1.0
	v_fmac_f32_e32 v62, v63, v62
	v_div_scale_f32 v63, vcc, v38, v60, v38
	v_mul_f32_e32 v64, v63, v62
	v_fma_f32 v65, -v61, v64, v63
	v_fmac_f32_e32 v64, v65, v62
	v_fma_f32 v61, -v61, v64, v63
	v_div_fmas_f32 v61, v61, v62, v64
	v_div_fixup_f32 v61, v61, v60, v38
	v_sub_f32_e32 v61, v61, v196
	ds_write_b32 v51, v61 offset:1088
	v_add_u32_e32 v60, 5, v57
	v_min_i32_e32 v60, s25, v60
	v_cvt_f32_i32_e32 v60, v60
	v_div_scale_f32 v61, s[28:29], v60, v60, v39
	v_rcp_f32_e32 v62, v61
	s_nop 0
	v_fma_f32 v63, -v61, v62, 1.0
	v_fmac_f32_e32 v62, v63, v62
	v_div_scale_f32 v63, vcc, v39, v60, v39
	v_mul_f32_e32 v64, v63, v62
	v_fma_f32 v65, -v61, v64, v63
	v_fmac_f32_e32 v64, v65, v62
	v_fma_f32 v61, -v61, v64, v63
	v_div_fmas_f32 v61, v61, v62, v64
	v_div_fixup_f32 v61, v61, v60, v39
	v_sub_f32_e32 v61, v61, v197
	ds_write_b32 v51, v61 offset:1360
	v_add_u32_e32 v60, 6, v57
	v_min_i32_e32 v60, s25, v60
	v_cvt_f32_i32_e32 v60, v60
	v_div_scale_f32 v61, s[28:29], v60, v60, v40
	v_rcp_f32_e32 v62, v61
	s_nop 0
	v_fma_f32 v63, -v61, v62, 1.0
	v_fmac_f32_e32 v62, v63, v62
	v_div_scale_f32 v63, vcc, v40, v60, v40
	v_mul_f32_e32 v64, v63, v62
	v_fma_f32 v65, -v61, v64, v63
	v_fmac_f32_e32 v64, v65, v62
	v_fma_f32 v61, -v61, v64, v63
	v_div_fmas_f32 v61, v61, v62, v64
	v_div_fixup_f32 v61, v61, v60, v40
	v_sub_f32_e32 v61, v61, v198
	ds_write_b32 v51, v61 offset:1632
	v_add_u32_e32 v60, 7, v57
	v_min_i32_e32 v60, s25, v60
	v_cvt_f32_i32_e32 v60, v60
	v_div_scale_f32 v61, s[28:29], v60, v60, v41
	v_rcp_f32_e32 v62, v61
	s_nop 0
	v_fma_f32 v63, -v61, v62, 1.0
	v_fmac_f32_e32 v62, v63, v62
	v_div_scale_f32 v63, vcc, v41, v60, v41
	v_mul_f32_e32 v64, v63, v62
	v_fma_f32 v65, -v61, v64, v63
	v_fmac_f32_e32 v64, v65, v62
	v_fma_f32 v61, -v61, v64, v63
	v_div_fmas_f32 v61, v61, v62, v64
	v_div_fixup_f32 v61, v61, v60, v41
	v_sub_f32_e32 v61, v61, v199
	ds_write_b32 v51, v61 offset:1904
	v_add_u32_e32 v60, 8, v57
	v_min_i32_e32 v60, s25, v60
	v_cvt_f32_i32_e32 v60, v60
	v_div_scale_f32 v61, s[28:29], v60, v60, v42
	v_rcp_f32_e32 v62, v61
	s_nop 0
	v_fma_f32 v63, -v61, v62, 1.0
	v_fmac_f32_e32 v62, v63, v62
	v_div_scale_f32 v63, vcc, v42, v60, v42
	v_mul_f32_e32 v64, v63, v62
	v_fma_f32 v65, -v61, v64, v63
	v_fmac_f32_e32 v64, v65, v62
	v_fma_f32 v61, -v61, v64, v63
	v_div_fmas_f32 v61, v61, v62, v64
	v_div_fixup_f32 v61, v61, v60, v42
	v_sub_f32_e32 v61, v61, v200
	ds_write_b32 v51, v61 offset:2176
	v_add_u32_e32 v60, 9, v57
	v_min_i32_e32 v60, s25, v60
	v_cvt_f32_i32_e32 v60, v60
	v_div_scale_f32 v61, s[28:29], v60, v60, v43
	v_rcp_f32_e32 v62, v61
	s_nop 0
	v_fma_f32 v63, -v61, v62, 1.0
	v_fmac_f32_e32 v62, v63, v62
	v_div_scale_f32 v63, vcc, v43, v60, v43
	v_mul_f32_e32 v64, v63, v62
	v_fma_f32 v65, -v61, v64, v63
	v_fmac_f32_e32 v64, v65, v62
	v_fma_f32 v61, -v61, v64, v63
	v_div_fmas_f32 v61, v61, v62, v64
	v_div_fixup_f32 v61, v61, v60, v43
	v_sub_f32_e32 v61, v61, v201
	ds_write_b32 v51, v61 offset:2448
	v_add_u32_e32 v60, 10, v57
	v_min_i32_e32 v60, s25, v60
	v_cvt_f32_i32_e32 v60, v60
	v_div_scale_f32 v61, s[28:29], v60, v60, v44
	v_rcp_f32_e32 v62, v61
	s_nop 0
	v_fma_f32 v63, -v61, v62, 1.0
	v_fmac_f32_e32 v62, v63, v62
	v_div_scale_f32 v63, vcc, v44, v60, v44
	v_mul_f32_e32 v64, v63, v62
	v_fma_f32 v65, -v61, v64, v63
	v_fmac_f32_e32 v64, v65, v62
	v_fma_f32 v61, -v61, v64, v63
	v_div_fmas_f32 v61, v61, v62, v64
	v_div_fixup_f32 v61, v61, v60, v44
	v_sub_f32_e32 v61, v61, v202
	ds_write_b32 v51, v61 offset:2720
	v_add_u32_e32 v60, 11, v57
	v_min_i32_e32 v60, s25, v60
	v_cvt_f32_i32_e32 v60, v60
	v_div_scale_f32 v61, s[28:29], v60, v60, v45
	v_rcp_f32_e32 v62, v61
	s_nop 0
	v_fma_f32 v63, -v61, v62, 1.0
	v_fmac_f32_e32 v62, v63, v62
	v_div_scale_f32 v63, vcc, v45, v60, v45
	v_mul_f32_e32 v64, v63, v62
	v_fma_f32 v65, -v61, v64, v63
	v_fmac_f32_e32 v64, v65, v62
	v_fma_f32 v61, -v61, v64, v63
	v_div_fmas_f32 v61, v61, v62, v64
	v_div_fixup_f32 v61, v61, v60, v45
	v_sub_f32_e32 v61, v61, v203
	ds_write_b32 v51, v61 offset:2992
	v_add_u32_e32 v60, 12, v57
	v_min_i32_e32 v60, s25, v60
	v_cvt_f32_i32_e32 v60, v60
	v_div_scale_f32 v61, s[28:29], v60, v60, v46
	v_rcp_f32_e32 v62, v61
	s_nop 0
	v_fma_f32 v63, -v61, v62, 1.0
	v_fmac_f32_e32 v62, v63, v62
	v_div_scale_f32 v63, vcc, v46, v60, v46
	v_mul_f32_e32 v64, v63, v62
	v_fma_f32 v65, -v61, v64, v63
	v_fmac_f32_e32 v64, v65, v62
	v_fma_f32 v61, -v61, v64, v63
	v_div_fmas_f32 v61, v61, v62, v64
	v_div_fixup_f32 v61, v61, v60, v46
	v_sub_f32_e32 v61, v61, v204
	ds_write_b32 v51, v61 offset:3264
	v_add_u32_e32 v60, 13, v57
	v_min_i32_e32 v60, s25, v60
	v_cvt_f32_i32_e32 v60, v60
	v_div_scale_f32 v61, s[28:29], v60, v60, v47
	v_rcp_f32_e32 v62, v61
	s_nop 0
	v_fma_f32 v63, -v61, v62, 1.0
	v_fmac_f32_e32 v62, v63, v62
	v_div_scale_f32 v63, vcc, v47, v60, v47
	v_mul_f32_e32 v64, v63, v62
	v_fma_f32 v65, -v61, v64, v63
	v_fmac_f32_e32 v64, v65, v62
	v_fma_f32 v61, -v61, v64, v63
	v_div_fmas_f32 v61, v61, v62, v64
	v_div_fixup_f32 v61, v61, v60, v47
	v_sub_f32_e32 v61, v61, v205
	ds_write_b32 v51, v61 offset:3536
	v_add_u32_e32 v60, 14, v57
	v_min_i32_e32 v60, s25, v60
	v_cvt_f32_i32_e32 v60, v60
	v_div_scale_f32 v61, s[28:29], v60, v60, v48
	v_rcp_f32_e32 v62, v61
	s_nop 0
	v_fma_f32 v63, -v61, v62, 1.0
	v_fmac_f32_e32 v62, v63, v62
	v_div_scale_f32 v63, vcc, v48, v60, v48
	v_mul_f32_e32 v64, v63, v62
	v_fma_f32 v65, -v61, v64, v63
	v_fmac_f32_e32 v64, v65, v62
	v_fma_f32 v61, -v61, v64, v63
	v_div_fmas_f32 v61, v61, v62, v64
	v_div_fixup_f32 v61, v61, v60, v48
	v_sub_f32_e32 v61, v61, v206
	ds_write_b32 v51, v61 offset:3808
	v_add_u32_e32 v60, 15, v57
	v_min_i32_e32 v60, s25, v60
	v_cvt_f32_i32_e32 v60, v60
	v_div_scale_f32 v61, s[28:29], v60, v60, v49
	v_rcp_f32_e32 v62, v61
	s_nop 0
	v_fma_f32 v63, -v61, v62, 1.0
	v_fmac_f32_e32 v62, v63, v62
	v_div_scale_f32 v63, vcc, v49, v60, v49
	v_mul_f32_e32 v64, v63, v62
	v_fma_f32 v65, -v61, v64, v63
	v_fmac_f32_e32 v64, v65, v62
	v_fma_f32 v61, -v61, v64, v63
	v_div_fmas_f32 v61, v61, v62, v64
	v_div_fixup_f32 v61, v61, v60, v49
	v_sub_f32_e32 v61, v61, v207
	ds_write_b32 v51, v61 offset:4080
	s_waitcnt lgkmcnt(0)
	s_barrier
; DI unsigned pk2(float lo, float hi) { f32x2 v = {lo, hi}; bf16x2_t r = __builtin_convertvector(v, bf16x2_t); return __builtin_bit_cast(unsigned, r); }
; DI void phase_pool(const Params& p, int l, char* smem) {
;     ...
;         {
;             const int t = tid >> 2, dq = (tid & 3) * 16;
;             float acc[16];
; #pragma unroll
;             for (int j = 0; j < 16; ++j) acc[j] = 0.f;
;             for (int c = 0; c < 64; ++c) {
;                 const float dv = sd[t * 65 + c];
; #pragma unroll
;                 for (int j4 = 0; j4 < 4; ++j4) {
;                     const f32x4 w4 = *(const f32x4*)(sw + c * 64 + dq + j4 * 4);
;                     acc[j4 * 4 + 0] += dv * w4[0]; acc[j4 * 4 + 1] += dv * w4[1]; acc[j4 * 4 + 2] += dv * w4[2]; acc[j4 * 4 + 3] += dv * w4[3];
;                 }
;             }
;             const float* sc = p.pool_scale + l * 256 + gi * 64 + dq;
;             u32x4 o0, o1;
; #pragma unroll
;             for (int j = 0; j < 4; ++j) { o0[j] = pk2(acc[2 * j] * sc[2 * j], acc[2 * j + 1] * sc[2 * j + 1]); o1[j] = pk2(acc[8 + 2 * j] * sc[8 + 2 * j], acc[9 + 2 * j] * sc[9 + 2 * j]); }
;             bf16_t* dst = p.hy + (n0 + t) * DM + 768 + gi * 64 + dq;
;             *(u32x4*)dst = o0; *(u32x4*)(dst + 8) = o1;
;         }
;         __syncthreads();
	ds_read_b128 v[58:61], v52 offset:0
	ds_read_b128 v[62:65], v52 offset:64
	ds_read_b128 v[66:69], v52 offset:128
	ds_read_b128 v[70:73], v52 offset:192
	s_waitcnt lgkmcnt(3)
	v_mfma_f32_16x16x4_f32 v[158:161], v77, v58, 0
	v_mfma_f32_16x16x4_f32 v[162:165], v78, v58, 0
	v_mfma_f32_16x16x4_f32 v[166:169], v79, v58, 0
	v_mfma_f32_16x16x4_f32 v[170:173], v80, v58, 0
	v_mfma_f32_16x16x4_f32 v[158:161], v81, v59, v[158:161]
	v_mfma_f32_16x16x4_f32 v[162:165], v82, v59, v[162:165]
	v_mfma_f32_16x16x4_f32 v[166:169], v83, v59, v[166:169]
	v_mfma_f32_16x16x4_f32 v[170:173], v84, v59, v[170:173]
	v_mfma_f32_16x16x4_f32 v[158:161], v85, v60, v[158:161]
	v_mfma_f32_16x16x4_f32 v[162:165], v86, v60, v[162:165]
	v_mfma_f32_16x16x4_f32 v[166:169], v87, v60, v[166:169]
	v_mfma_f32_16x16x4_f32 v[170:173], v88, v60, v[170:173]
	v_mfma_f32_16x16x4_f32 v[158:161], v89, v61, v[158:161]
	v_mfma_f32_16x16x4_f32 v[162:165], v90, v61, v[162:165]
	v_mfma_f32_16x16x4_f32 v[166:169], v91, v61, v[166:169]
	v_mfma_f32_16x16x4_f32 v[170:173], v92, v61, v[170:173]
	s_waitcnt lgkmcnt(2)
	v_mfma_f32_16x16x4_f32 v[158:161], v93, v62, v[158:161]
	v_mfma_f32_16x16x4_f32 v[162:165], v94, v62, v[162:165]
	v_mfma_f32_16x16x4_f32 v[166:169], v95, v62, v[166:169]
	v_mfma_f32_16x16x4_f32 v[170:173], v96, v62, v[170:173]
	v_mfma_f32_16x16x4_f32 v[158:161], v97, v63, v[158:161]
	v_mfma_f32_16x16x4_f32 v[162:165], v98, v63, v[162:165]
	v_mfma_f32_16x16x4_f32 v[166:169], v99, v63, v[166:169]
	v_mfma_f32_16x16x4_f32 v[170:173], v100, v63, v[170:173]
	v_mfma_f32_16x16x4_f32 v[158:161], v101, v64, v[158:161]
	v_mfma_f32_16x16x4_f32 v[162:165], v102, v64, v[162:165]
	v_mfma_f32_16x16x4_f32 v[166:169], v103, v64, v[166:169]
	v_mfma_f32_16x16x4_f32 v[170:173], v104, v64, v[170:173]
	v_mfma_f32_16x16x4_f32 v[158:161], v105, v65, v[158:161]
	v_mfma_f32_16x16x4_f32 v[162:165], v106, v65, v[162:165]
	v_mfma_f32_16x16x4_f32 v[166:169], v107, v65, v[166:169]
	v_mfma_f32_16x16x4_f32 v[170:173], v108, v65, v[170:173]
	s_waitcnt lgkmcnt(1)
	v_mfma_f32_16x16x4_f32 v[158:161], v109, v66, v[158:161]
	v_mfma_f32_16x16x4_f32 v[162:165], v110, v66, v[162:165]
	v_mfma_f32_16x16x4_f32 v[166:169], v111, v66, v[166:169]
	v_mfma_f32_16x16x4_f32 v[170:173], v112, v66, v[170:173]
	v_mfma_f32_16x16x4_f32 v[158:161], v113, v67, v[158:161]
	v_mfma_f32_16x16x4_f32 v[162:165], v114, v67, v[162:165]
	v_mfma_f32_16x16x4_f32 v[166:169], v115, v67, v[166:169]
	v_mfma_f32_16x16x4_f32 v[170:173], v116, v67, v[170:173]
	v_mfma_f32_16x16x4_f32 v[158:161], v117, v68, v[158:161]
	v_mfma_f32_16x16x4_f32 v[162:165], v118, v68, v[162:165]
	v_mfma_f32_16x16x4_f32 v[166:169], v119, v68, v[166:169]
	v_mfma_f32_16x16x4_f32 v[170:173], v120, v68, v[170:173]
	v_mfma_f32_16x16x4_f32 v[158:161], v121, v69, v[158:161]
	v_mfma_f32_16x16x4_f32 v[162:165], v122, v69, v[162:165]
	v_mfma_f32_16x16x4_f32 v[166:169], v123, v69, v[166:169]
	v_mfma_f32_16x16x4_f32 v[170:173], v124, v69, v[170:173]
	s_waitcnt lgkmcnt(0)
	v_mfma_f32_16x16x4_f32 v[158:161], v125, v70, v[158:161]
	v_mfma_f32_16x16x4_f32 v[162:165], v126, v70, v[162:165]
	v_mfma_f32_16x16x4_f32 v[166:169], v127, v70, v[166:169]
	v_mfma_f32_16x16x4_f32 v[170:173], v128, v70, v[170:173]
	v_mfma_f32_16x16x4_f32 v[158:161], v129, v71, v[158:161]
	v_mfma_f32_16x16x4_f32 v[162:165], v130, v71, v[162:165]
	v_mfma_f32_16x16x4_f32 v[166:169], v131, v71, v[166:169]
	v_mfma_f32_16x16x4_f32 v[170:173], v132, v71, v[170:173]
	v_mfma_f32_16x16x4_f32 v[158:161], v133, v72, v[158:161]
	v_mfma_f32_16x16x4_f32 v[162:165], v134, v72, v[162:165]
	v_mfma_f32_16x16x4_f32 v[166:169], v135, v72, v[166:169]
	v_mfma_f32_16x16x4_f32 v[170:173], v136, v72, v[170:173]
	v_mfma_f32_16x16x4_f32 v[158:161], v137, v73, v[158:161]
	v_mfma_f32_16x16x4_f32 v[162:165], v138, v73, v[162:165]
	v_mfma_f32_16x16x4_f32 v[166:169], v139, v73, v[166:169]
	v_mfma_f32_16x16x4_f32 v[170:173], v140, v73, v[170:173]
	v_lshl_add_u64 v[74:75], s[16:17], 0, v[22:23]
	v_readlane_b32 s52, v250, 51
	v_lshlrev_b64 v[74:75], 11, v[74:75]
	v_readlane_b32 s54, v250, 53
	v_readlane_b32 s55, v250, 54
	s_lshl_b32 s30, s23, 7
	s_and_b64 vcc, exec, s[14:15]
	v_lshl_add_u64 v[74:75], s[54:55], 0, v[74:75]
	v_lshl_add_u64 v[74:75], v[74:75], 0, s[30:31]
	s_mov_b32 s20, s24
	v_lshl_add_u64 v[74:75], v[74:75], 0, v[188:189]
	v_readlane_b32 s53, v250, 52
	v_readlane_b32 s56, v250, 55
	v_readlane_b32 s57, v250, 56
	v_readlane_b32 s58, v250, 57
	v_readlane_b32 s59, v250, 58
	v_readlane_b32 s60, v250, 59
	v_readlane_b32 s61, v250, 60
	v_readlane_b32 s62, v250, 61
	v_readlane_b32 s63, v250, 62
	v_readlane_b32 s64, v250, 63
	v_readlane_b32 s65, v249, 0
	v_readlane_b32 s66, v249, 1
	v_readlane_b32 s67, v249, 2
	s_nop 15
	v_pk_mul_f32 v[158:159], v[158:159], v[142:143]
	v_pk_mul_f32 v[160:161], v[160:161], v[144:145]
	v_pk_mul_f32 v[162:163], v[162:163], v[146:147]
	v_pk_mul_f32 v[164:165], v[164:165], v[148:149]
	v_pk_mul_f32 v[166:167], v[166:167], v[150:151]
	v_pk_mul_f32 v[168:169], v[168:169], v[152:153]
	v_pk_mul_f32 v[170:171], v[170:171], v[154:155]
	v_pk_mul_f32 v[172:173], v[172:173], v[156:157]
	v_cvt_pk_bf16_f32 v34, v158, v159
	v_cvt_pk_bf16_f32 v35, v160, v161
	v_cvt_pk_bf16_f32 v36, v162, v163
	v_cvt_pk_bf16_f32 v37, v164, v165
	v_cvt_pk_bf16_f32 v38, v166, v167
	v_cvt_pk_bf16_f32 v39, v168, v169
	v_cvt_pk_bf16_f32 v40, v170, v171
	v_cvt_pk_bf16_f32 v41, v172, v173
	global_store_dwordx4 v[74:75], v[34:37], off offset:1536
	global_store_dwordx4 v[74:75], v[38:41], off offset:1552
	s_cbranch_vccz .LBB0_375
	s_branch .LBB0_397

; DI int tid_() { int t = threadIdx.x; asm volatile("" : "+v"(t)); return t; }
; DI void nsa_item(const Params& p, int bk, int qb, char* smem, float Mb) {
;     const int tid = tid_(), lane = tid & 63, wave = __builtin_amdgcn_readfirstlane(tid >> 6), fr = lane & 15, fq = lane >> 4;
;     const int b = bk >> 1, kvh = bk & 1, cur = qb;
;     const int t0 = qb * 64 + wave * 16;
;     const size_t n0 = (size_t)b * T_ + t0, nb0 = (size_t)b * T_ + qb * 64;
;     float* imp = (float*)(smem + wave * 17664);
;     int* sel = (int*)(smem + wave * 17664 + 16640);
;     unsigned long long* masks = (unsigned long long*)(smem + 70656);
;     float* acc = (float*)smem;
;     float* accl = acc + 64 * 193;
;     const bf16_t* gatep = p.proj + (n0 + fr) * DINP + C_GATE + kvh * 9;
;     const int tq = t0 + fr;
;     const int nforced = cur >= 2 ? 3 : cur + 1;
;     {
;         const int nv = tq >= 31 ? ((tq - 31) >> 4) + 1 : 0;
;         const int nvmax = t0 >= 16 ? (t0 >> 4) : 0;
;         const int ntile = (nvmax + 63) >> 6;
;         const bf16_t* KCp = p.kc + (size_t)bk * 1024 * 64;
;         const bf16_t* VCp = p.vct + (size_t)bk * 16 * 4096;
;         bf16x8 qf[3][2];
; #pragma unroll
;         for (int g = 0; g < 3; ++g) {
;             qf[g][0] = *(const bf16x8*)(p.qn + ((n0 + fr) * 6 + kvh * 3 + g) * 64 + fq * 8);
;             qf[g][1] = *(const bf16x8*)(p.qn + ((n0 + fr) * 6 + kvh * 3 + g) * 64 + 32 + fq * 8);
;         }
;         float m[3], ls[3];
; #pragma unroll
;         for (int g = 0; g < 3; ++g) { m[g] = -1e30f; ls[g] = 0.f; }
;         {
;             bf16x8 kn[4][2];
;             if (ntile > 0) ldfrag(KCp, fr, fq, kn);
; DI void phase_nsa(const Params& p, int l, int first, char* smem) {
;     ...
;         if (tid_() == 0) *slot = atomicAdd(p.nsa_ctr + l * 4 + bk, 1);
;         __syncthreads();
;         const int i = *slot;
;         if (i >= 256) break;
;         nsa_item(p, bk, 255 - i, smem, Mb);
.LBB0_462:
	s_or_b64 exec, exec, s[4:5]
	s_add_i32 s4, 0, 0x11c00
	s_cmp_lg_u32 s4, -1
	s_cselect_b32 s4, s4, 0
	s_cselect_b32 s5, s69, 0
	v_mov_b32_e32 v0, s4
	v_mov_b32_e32 v1, s5
	s_waitcnt lgkmcnt(0)
	s_barrier
	flat_load_dword v142, v[0:1] sc0 sc1
	s_waitcnt vmcnt(0)
	s_movk_i32 s4, 0x100
	s_waitcnt lgkmcnt(0)
	v_cmp_gt_i32_e32 vcc, s4, v142
	s_mov_b64 s[4:5], -1
	s_and_saveexec_b64 s[48:49], vcc
	s_cbranch_execz .LBB0_457
	v_mov_b32_e32 v237, v210
	v_sub_u32_e32 v238, 0xff, v142
	v_readfirstlane_b32 s4, v237
	s_ashr_i32 s30, s4, 6
	s_lshl_b32 s93, s30, 4
	v_lshl_add_u32 v192, v238, 6, s93
	v_readlane_b32 s4, v249, 5
	v_ashrrev_i32_e32 v193, 31, v192
	v_readlane_b32 s5, v249, 6
	v_and_b32_e32 v236, 15, v237
	v_and_b32_e32 v194, 48, v237
	v_lshl_add_u64 v[136:137], v[192:193], 0, s[4:5]
	v_readlane_b32 s4, v249, 7
	v_or_b32_e32 v136, v136, v236
	v_readlane_b32 s5, v249, 8
	v_mov_b32_e32 v195, v189
	v_or_b32_e32 v193, v192, v236
	v_mad_u64_u32 v[0:1], s[4:5], v136, 6, s[4:5]
	v_mad_i32_i24 v1, v137, 6, v1
	v_readlane_b32 s4, v250, 51
	v_lshlrev_b64 v[0:1], 7, v[0:1]
	v_readlane_b32 s18, v249, 1
	v_readlane_b32 s19, v249, 2
	v_subrev_u32_e32 v24, 31, v193
	v_max_i32_e32 v25, 15, v192
	v_lshl_add_u64 v[0:1], s[18:19], 0, v[0:1]
	v_lshl_add_u64 v[200:201], v[0:1], 0, v[194:195]
	global_load_dwordx4 v[0:3], v[200:201], off
	global_load_dwordx4 v[4:7], v[200:201], off offset:64
	global_load_dwordx4 v[8:11], v[200:201], off offset:128
	global_load_dwordx4 v[12:15], v[200:201], off offset:192
	global_load_dwordx4 v[16:19], v[200:201], off offset:256
	global_load_dwordx4 v[20:23], v[200:201], off offset:320
	v_ashrrev_i32_e32 v24, 4, v24
	v_lshrrev_b32_e32 v96, 4, v25
	v_readlane_b32 s5, v250, 52
	v_bfe_u32 v143, v237, 4, 2
	v_add_u32_e32 v24, 1, v24
	v_add_u32_e32 v25, 63, v96
	v_cmp_lt_i32_e32 vcc, 30, v193
	v_lshlrev_b32_e32 v94, 3, v143
	v_lshrrev_b32_e32 v95, 6, v25
	v_cndmask_b32_e32 v144, 0, v24, vcc
	v_cmp_lt_i32_e64 s[4:5], 15, v192
	v_mov_b32_e32 v148, 0xf149f2ca
	v_mov_b32_e32 v93, 0
	v_mov_b32_e32 v92, 0
	v_mov_b32_e32 v147, 0xf149f2ca
	v_mov_b32_e32 v145, 0xf149f2ca
	v_mov_b32_e32 v101, 0
	v_readlane_b32 s6, v250, 53
	v_readlane_b32 s7, v250, 54
	v_readlane_b32 s8, v250, 55
	v_readlane_b32 s9, v250, 56
	v_readlane_b32 s10, v250, 57
	v_readlane_b32 s11, v250, 58
	v_readlane_b32 s12, v250, 59
	v_readlane_b32 s13, v250, 60
	v_readlane_b32 s14, v250, 61
	v_readlane_b32 s15, v250, 62
	v_readlane_b32 s16, v250, 63
	v_readlane_b32 s17, v249, 0
	s_and_saveexec_b64 s[86:87], s[4:5]
	s_cbranch_execz .LBB0_471
	v_readlane_b32 s6, v250, 17
	v_lshlrev_b32_e32 v188, 7, v236
	v_readlane_b32 s7, v250, 18
	v_lshlrev_b32_e32 v90, 1, v94
	v_mov_b32_e32 v91, v189
	v_lshl_add_u64 v[88:89], s[6:7], 0, v[188:189]
	v_lshl_add_u64 v[24:25], v[88:89], 0, v[90:91]
	global_load_dwordx4 v[84:87], v[24:25], off
	global_load_dwordx4 v[80:83], v[24:25], off offset:64
	global_load_dwordx4 v[76:79], v[24:25], off offset:2048
	global_load_dwordx4 v[72:75], v[24:25], off offset:2112
	v_add_co_u32_e32 v24, vcc, 0x1000, v24
	s_mov_b32 s6, 0
	s_nop 0
	v_addc_co_u32_e32 v25, vcc, 0, v25, vcc
	global_load_dwordx4 v[68:71], v[24:25], off
	global_load_dwordx4 v[64:67], v[24:25], off offset:64
	global_load_dwordx4 v[60:63], v[24:25], off offset:2048
	global_load_dwordx4 v[56:59], v[24:25], off offset:2112
	v_max_u32_e32 v24, 1, v95
	v_lshlrev_b32_e32 v97, 2, v143
	v_lshlrev_b32_e32 v98, 6, v24
	v_mov_b32_e32 v105, 0xf149f2ca
	v_mov_b32_e32 v104, 0
	s_mov_b64 s[88:89], 0
	v_mov_b32_e32 v102, 0
	v_mov_b32_e32 v99, 0
	v_mov_b32_e32 v103, 0xf149f2ca
	v_mov_b32_e32 v100, 0xf149f2ca
	s_mov_b32 s94, 0
	s_branch .LBB0_466
.Ltramp_153:
	s_branch .LBB0_153

; DI void nsa_item(const Params& p, int bk, int qb, char* smem, float Mb) {
;     ...
;             for (int kt = 0; kt < ntile; ++kt) {
;                 bf16x8 kf[4][2];
; #pragma unroll
;                 for (int k4 = 0; k4 < 4; ++k4) { kf[k4][0] = kn[k4][0]; kf[k4][1] = kn[k4][1]; }
;                 ldfrag(KCp + (kt + 1 < ntile ? kt + 1 : kt) * 4096, fr, fq, kn);
;                 unsigned vm = 0;
; #pragma unroll
;                 for (int k4 = 0; k4 < 4; ++k4)
; #pragma unroll
;                     for (int ii = 0; ii < 4; ++ii) if (kt * 64 + k4 * 16 + fq * 4 + ii < nv) vm |= 1u << (k4 * 4 + ii);
;                 const bool full = (kt + 1) * 64 <= nvmax - 1;
;                 if (full) {
; #pragma unroll
;                     for (int g = 0; g < 3; ++g) { f32x4 st[4]; st_from(kf, qf[g], st); stats_step<true>(st, vm, m[g], ls[g]); }
;                 } else {
; #pragma unroll
;                     for (int g = 0; g < 3; ++g) { f32x4 st[4]; st_from(kf, qf[g], st); stats_step(st, vm, m[g], ls[g]); }
;                 }
;             }
.Ltramp_935:
	s_branch .LBB0_935
.LBB0_465:
	s_or_b64 exec, exec, s[6:7]
	s_waitcnt vmcnt(8)
	v_sub_f32_e32 v56, v100, v148
	v_exp_f32_e32 v56, v56
	v_cmp_eq_u32_e32 vcc, s95, v98
	s_waitcnt vmcnt(7)
	v_mov_b64_e32 v[86:87], v[26:27]
	s_waitcnt vmcnt(6)
	v_mov_b64_e32 v[82:83], v[30:31]
	v_fmac_f32_e32 v92, v99, v56
	s_waitcnt vmcnt(5)
	v_mov_b64_e32 v[78:79], v[34:35]
	s_waitcnt vmcnt(4)
	v_mov_b64_e32 v[74:75], v[38:39]
	s_waitcnt vmcnt(3)
	v_mov_b64_e32 v[70:71], v[42:43]
	s_waitcnt vmcnt(2)
	v_mov_b64_e32 v[66:67], v[46:47]
	s_waitcnt vmcnt(1)
	v_mov_b64_e32 v[62:63], v[50:51]
	s_waitcnt vmcnt(0)
	v_mov_b64_e32 v[58:59], v[54:55]
	s_or_b64 s[88:89], vcc, s[88:89]
	s_mov_b32 s6, s95
	v_mov_b64_e32 v[84:85], v[24:25]
	v_mov_b64_e32 v[80:81], v[28:29]
	v_mov_b64_e32 v[76:77], v[32:33]
	v_mov_b64_e32 v[72:73], v[36:37]
	v_mov_b64_e32 v[68:69], v[40:41]
	v_mov_b64_e32 v[64:65], v[44:45]
	v_mov_b64_e32 v[60:61], v[48:49]
	v_mov_b64_e32 v[56:57], v[52:53]
	v_mov_b32_e32 v104, v101
	v_mov_b32_e32 v102, v93
	v_mov_b32_e32 v99, v92
	v_mov_b32_e32 v105, v145
	v_mov_b32_e32 v103, v147
	v_mov_b32_e32 v100, v148
	s_andn2_b64 exec, exec, s[88:89]
	s_cbranch_execz .LBB0_470
